# window-attention (4 sites): diagonal-band bias-table reads batched and unconditional with add + select, same rewrite as the diff loop
# baseline (speedup 1.0000x reference)
; __device__ __forceinline__ void bias_mask_tile(f32x16& p0, f32x16& p1, int dq, unsigned W, const float* tbx) {
;     const float NEG = -__builtin_inff();
;     const float* bp = tbx + (dq - 63);
; #pragma unroll
;     for (int r = 0; r < 16; ++r) {
;         const int c = (r & 3) + 8 * (r >> 2);
;         const unsigned r0 = (unsigned)(dq - c), r1 = (unsigned)(dq - c - 32);
;         const float b0 = bp[63 - c], b1 = bp[31 - c];
;         p0[r] = r0 >= W ? NEG : p0[r] + b0;
;         p1[r] = r1 >= W ? NEG : p1[r] + b1;
;         if ((r & 3) == 3) __builtin_amdgcn_sched_barrier(0);
;     }
; }
.LBB0_645:
	s_bfe_u32 s20, s27, 0x30006
	s_mulk_i32 s20, 0x880
	s_add_i32 s29, s20, 0
	s_andn2_b64 vcc, exec, s[2:3]
	s_add_i32 s29, s29, 0x14800
	s_cbranch_vccnz .LBB0_679
	v_subrev_u32_e32 v63, s10, v174
	v_lshl_add_u32 v49, v63, 2, s29
	ds_read_b32 v16, v49 offset:1280
	ds_read_b32 v17, v49 offset:1276
	ds_read_b32 v18, v49 offset:1272
	ds_read_b32 v19, v49 offset:1268
	ds_read_b32 v20, v49 offset:1248
	ds_read_b32 v21, v49 offset:1244
	ds_read_b32 v22, v49 offset:1240
	ds_read_b32 v23, v49 offset:1236
	ds_read_b32 v24, v49 offset:1216
	ds_read_b32 v25, v49 offset:1212
	ds_read_b32 v26, v49 offset:1208
	ds_read_b32 v27, v49 offset:1204
	ds_read_b32 v28, v49 offset:1184
	ds_read_b32 v29, v49 offset:1180
	ds_read_b32 v30, v49 offset:1176
	ds_read_b32 v31, v49 offset:1172
	s_waitcnt lgkmcnt(0)
	v_cmp_gt_u32_e32 vcc, s57, v63
	v_add_f32_e32 v16, v32, v16
	v_subrev_u32_e32 v237, 1, v63
	v_cndmask_b32_e32 v16, v166, v16, vcc
	v_cmp_gt_u32_e32 vcc, s57, v237
	v_add_f32_e32 v17, v33, v17
	v_subrev_u32_e32 v236, 2, v63
	v_cndmask_b32_e32 v17, v166, v17, vcc
	v_cmp_gt_u32_e32 vcc, s57, v236
	v_add_f32_e32 v18, v34, v18
	v_subrev_u32_e32 v237, 3, v63
	v_cndmask_b32_e32 v18, v166, v18, vcc
	v_cmp_gt_u32_e32 vcc, s57, v237
	v_add_f32_e32 v19, v35, v19
	v_subrev_u32_e32 v236, 8, v63
	v_cndmask_b32_e32 v19, v166, v19, vcc
	v_cmp_gt_u32_e32 vcc, s57, v236
	v_add_f32_e32 v20, v36, v20
	v_subrev_u32_e32 v237, 9, v63
	v_cndmask_b32_e32 v20, v166, v20, vcc
	v_cmp_gt_u32_e32 vcc, s57, v237
	v_add_f32_e32 v21, v37, v21
	v_subrev_u32_e32 v236, 10, v63
	v_cndmask_b32_e32 v21, v166, v21, vcc
	v_cmp_gt_u32_e32 vcc, s57, v236
	v_add_f32_e32 v22, v38, v22
	v_subrev_u32_e32 v237, 11, v63
	v_cndmask_b32_e32 v22, v166, v22, vcc
	v_cmp_gt_u32_e32 vcc, s57, v237
	v_add_f32_e32 v23, v39, v23
	v_subrev_u32_e32 v236, 16, v63
	v_cndmask_b32_e32 v23, v166, v23, vcc
	v_cmp_gt_u32_e32 vcc, s57, v236
	v_add_f32_e32 v24, v40, v24
	v_subrev_u32_e32 v237, 17, v63
	v_cndmask_b32_e32 v24, v166, v24, vcc
	v_cmp_gt_u32_e32 vcc, s57, v237
	v_add_f32_e32 v25, v41, v25
	v_subrev_u32_e32 v236, 18, v63
	v_cndmask_b32_e32 v25, v166, v25, vcc
	v_cmp_gt_u32_e32 vcc, s57, v236
	v_add_f32_e32 v26, v42, v26
	v_subrev_u32_e32 v237, 19, v63
	v_cndmask_b32_e32 v26, v166, v26, vcc
	v_cmp_gt_u32_e32 vcc, s57, v237
	v_add_f32_e32 v27, v43, v27
	v_subrev_u32_e32 v236, 24, v63
	v_cndmask_b32_e32 v27, v166, v27, vcc
	v_cmp_gt_u32_e32 vcc, s57, v236
	v_add_f32_e32 v28, v44, v28
	v_subrev_u32_e32 v237, 25, v63
	v_cndmask_b32_e32 v28, v166, v28, vcc
	v_cmp_gt_u32_e32 vcc, s57, v237
	v_add_f32_e32 v29, v45, v29
	v_subrev_u32_e32 v236, 26, v63
	v_cndmask_b32_e32 v29, v166, v29, vcc
	v_cmp_gt_u32_e32 vcc, s57, v236
	v_add_f32_e32 v30, v46, v30
	v_subrev_u32_e32 v237, 27, v63
	v_cndmask_b32_e32 v30, v166, v30, vcc
	v_cmp_gt_u32_e32 vcc, s57, v237
	v_add_f32_e32 v31, v47, v31
	s_nop 0
	v_cndmask_b32_e32 v31, v166, v31, vcc
	ds_read_b32 v32, v49 offset:1152
	ds_read_b32 v33, v49 offset:1148
	ds_read_b32 v34, v49 offset:1144
	ds_read_b32 v35, v49 offset:1140
	ds_read_b32 v36, v49 offset:1120
	ds_read_b32 v37, v49 offset:1116
	ds_read_b32 v38, v49 offset:1112
	ds_read_b32 v39, v49 offset:1108
	ds_read_b32 v40, v49 offset:1088
	ds_read_b32 v41, v49 offset:1084
	ds_read_b32 v42, v49 offset:1080
	ds_read_b32 v43, v49 offset:1076
	ds_read_b32 v44, v49 offset:1056
	ds_read_b32 v45, v49 offset:1052
	ds_read_b32 v46, v49 offset:1048
	ds_read_b32 v47, v49 offset:1044
	s_waitcnt lgkmcnt(0)
	v_subrev_u32_e32 v236, 32, v63
	v_cmp_gt_u32_e32 vcc, s57, v236
	v_add_f32_e32 v48, v0, v32
	v_subrev_u32_e32 v237, 33, v63
	v_cndmask_b32_e32 v48, v166, v48, vcc
	v_cmp_gt_u32_e32 vcc, s57, v237
	v_add_f32_e32 v49, v1, v33
	v_subrev_u32_e32 v236, 34, v63
	v_cndmask_b32_e32 v49, v166, v49, vcc
	v_cmp_gt_u32_e32 vcc, s57, v236
	v_add_f32_e32 v50, v2, v34
	v_subrev_u32_e32 v237, 35, v63
	v_cndmask_b32_e32 v50, v166, v50, vcc
	v_cmp_gt_u32_e32 vcc, s57, v237
	v_add_f32_e32 v51, v3, v35
	v_subrev_u32_e32 v236, 40, v63
	v_cndmask_b32_e32 v51, v166, v51, vcc
	v_cmp_gt_u32_e32 vcc, s57, v236
	v_add_f32_e32 v52, v4, v36
	v_subrev_u32_e32 v237, 41, v63
	v_cndmask_b32_e32 v52, v166, v52, vcc
	v_cmp_gt_u32_e32 vcc, s57, v237
	v_add_f32_e32 v53, v5, v37
	v_subrev_u32_e32 v236, 42, v63
	v_cndmask_b32_e32 v53, v166, v53, vcc
	v_cmp_gt_u32_e32 vcc, s57, v236
	v_add_f32_e32 v54, v6, v38
	v_subrev_u32_e32 v237, 43, v63
	v_cndmask_b32_e32 v54, v166, v54, vcc
	v_cmp_gt_u32_e32 vcc, s57, v237
	v_add_f32_e32 v55, v7, v39
	v_subrev_u32_e32 v236, 48, v63
	v_cndmask_b32_e32 v55, v166, v55, vcc
	v_cmp_gt_u32_e32 vcc, s57, v236
	v_add_f32_e32 v56, v8, v40
	v_subrev_u32_e32 v237, 49, v63
	v_cndmask_b32_e32 v56, v166, v56, vcc
	v_cmp_gt_u32_e32 vcc, s57, v237
	v_add_f32_e32 v57, v9, v41
	v_subrev_u32_e32 v236, 50, v63
	v_cndmask_b32_e32 v57, v166, v57, vcc
	v_cmp_gt_u32_e32 vcc, s57, v236
	v_add_f32_e32 v58, v10, v42
	v_subrev_u32_e32 v237, 51, v63
	v_cndmask_b32_e32 v58, v166, v58, vcc
	v_cmp_gt_u32_e32 vcc, s57, v237
	v_add_f32_e32 v59, v11, v43
	v_subrev_u32_e32 v236, 56, v63
	v_cndmask_b32_e32 v59, v166, v59, vcc
	v_cmp_gt_u32_e32 vcc, s57, v236
	v_add_f32_e32 v60, v12, v44
	v_subrev_u32_e32 v237, 57, v63
	v_cndmask_b32_e32 v60, v166, v60, vcc
	v_cmp_gt_u32_e32 vcc, s57, v237
	v_add_f32_e32 v61, v13, v45
	v_subrev_u32_e32 v236, 58, v63
	v_cndmask_b32_e32 v61, v166, v61, vcc
	v_cmp_gt_u32_e32 vcc, s57, v236
	v_add_f32_e32 v62, v14, v46
	v_subrev_u32_e32 v237, 59, v63
	v_cndmask_b32_e32 v62, v166, v62, vcc
	v_cmp_gt_u32_e32 vcc, s57, v237
	v_add_f32_e32 v63, v15, v47
	s_nop 0
	v_cndmask_b32_e32 v63, v166, v63, vcc

; __device__ __forceinline__ void bias_mask_tile(f32x16& p0, f32x16& p1, int dq, unsigned W, const float* tbx) {
;     const float NEG = -__builtin_inff();
;     const float* bp = tbx + (dq - 63);
; #pragma unroll
;     for (int r = 0; r < 16; ++r) {
;         const int c = (r & 3) + 8 * (r >> 2);
;         const unsigned r0 = (unsigned)(dq - c), r1 = (unsigned)(dq - c - 32);
;         const float b0 = bp[63 - c], b1 = bp[31 - c];
;         p0[r] = r0 >= W ? NEG : p0[r] + b0;
;         p1[r] = r1 >= W ? NEG : p1[r] + b1;
;         if ((r & 3) == 3) __builtin_amdgcn_sched_barrier(0);
;     }
; }
.LBB0_685:
	s_andn2_b64 vcc, exec, s[4:5]
	s_cbranch_vccnz .LBB0_719
	v_subrev_u32_e32 v127, s20, v174
	v_lshl_add_u32 v113, v127, 2, s29
	ds_read_b32 v96, v113 offset:1280
	ds_read_b32 v97, v113 offset:1276
	ds_read_b32 v98, v113 offset:1272
	ds_read_b32 v99, v113 offset:1268
	ds_read_b32 v100, v113 offset:1248
	ds_read_b32 v101, v113 offset:1244
	ds_read_b32 v102, v113 offset:1240
	ds_read_b32 v103, v113 offset:1236
	ds_read_b32 v104, v113 offset:1216
	ds_read_b32 v105, v113 offset:1212
	ds_read_b32 v106, v113 offset:1208
	ds_read_b32 v107, v113 offset:1204
	ds_read_b32 v108, v113 offset:1184
	ds_read_b32 v109, v113 offset:1180
	ds_read_b32 v110, v113 offset:1176
	ds_read_b32 v111, v113 offset:1172
	s_waitcnt lgkmcnt(0)
	v_cmp_gt_u32_e32 vcc, s57, v127
	v_add_f32_e32 v96, v80, v96
	v_subrev_u32_e32 v237, 1, v127
	v_cndmask_b32_e32 v96, v166, v96, vcc
	v_cmp_gt_u32_e32 vcc, s57, v237
	v_add_f32_e32 v97, v81, v97
	v_subrev_u32_e32 v236, 2, v127
	v_cndmask_b32_e32 v97, v166, v97, vcc
	v_cmp_gt_u32_e32 vcc, s57, v236
	v_add_f32_e32 v98, v82, v98
	v_subrev_u32_e32 v237, 3, v127
	v_cndmask_b32_e32 v98, v166, v98, vcc
	v_cmp_gt_u32_e32 vcc, s57, v237
	v_add_f32_e32 v99, v83, v99
	v_subrev_u32_e32 v236, 8, v127
	v_cndmask_b32_e32 v99, v166, v99, vcc
	v_cmp_gt_u32_e32 vcc, s57, v236
	v_add_f32_e32 v100, v84, v100
	v_subrev_u32_e32 v237, 9, v127
	v_cndmask_b32_e32 v100, v166, v100, vcc
	v_cmp_gt_u32_e32 vcc, s57, v237
	v_add_f32_e32 v101, v85, v101
	v_subrev_u32_e32 v236, 10, v127
	v_cndmask_b32_e32 v101, v166, v101, vcc
	v_cmp_gt_u32_e32 vcc, s57, v236
	v_add_f32_e32 v102, v86, v102
	v_subrev_u32_e32 v237, 11, v127
	v_cndmask_b32_e32 v102, v166, v102, vcc
	v_cmp_gt_u32_e32 vcc, s57, v237
	v_add_f32_e32 v103, v87, v103
	v_subrev_u32_e32 v236, 16, v127
	v_cndmask_b32_e32 v103, v166, v103, vcc
	v_cmp_gt_u32_e32 vcc, s57, v236
	v_add_f32_e32 v104, v88, v104
	v_subrev_u32_e32 v237, 17, v127
	v_cndmask_b32_e32 v104, v166, v104, vcc
	v_cmp_gt_u32_e32 vcc, s57, v237
	v_add_f32_e32 v105, v89, v105
	v_subrev_u32_e32 v236, 18, v127
	v_cndmask_b32_e32 v105, v166, v105, vcc
	v_cmp_gt_u32_e32 vcc, s57, v236
	v_add_f32_e32 v106, v90, v106
	v_subrev_u32_e32 v237, 19, v127
	v_cndmask_b32_e32 v106, v166, v106, vcc
	v_cmp_gt_u32_e32 vcc, s57, v237
	v_add_f32_e32 v107, v91, v107
	v_subrev_u32_e32 v236, 24, v127
	v_cndmask_b32_e32 v107, v166, v107, vcc
	v_cmp_gt_u32_e32 vcc, s57, v236
	v_add_f32_e32 v108, v92, v108
	v_subrev_u32_e32 v237, 25, v127
	v_cndmask_b32_e32 v108, v166, v108, vcc
	v_cmp_gt_u32_e32 vcc, s57, v237
	v_add_f32_e32 v109, v93, v109
	v_subrev_u32_e32 v236, 26, v127
	v_cndmask_b32_e32 v109, v166, v109, vcc
	v_cmp_gt_u32_e32 vcc, s57, v236
	v_add_f32_e32 v110, v94, v110
	v_subrev_u32_e32 v237, 27, v127
	v_cndmask_b32_e32 v110, v166, v110, vcc
	v_cmp_gt_u32_e32 vcc, s57, v237
	v_add_f32_e32 v111, v95, v111
	s_nop 0
	v_cndmask_b32_e32 v111, v166, v111, vcc
	ds_read_b32 v80, v113 offset:1152
	ds_read_b32 v81, v113 offset:1148
	ds_read_b32 v82, v113 offset:1144
	ds_read_b32 v83, v113 offset:1140
	ds_read_b32 v84, v113 offset:1120
	ds_read_b32 v85, v113 offset:1116
	ds_read_b32 v86, v113 offset:1112
	ds_read_b32 v87, v113 offset:1108
	ds_read_b32 v88, v113 offset:1088
	ds_read_b32 v89, v113 offset:1084
	ds_read_b32 v90, v113 offset:1080
	ds_read_b32 v91, v113 offset:1076
	ds_read_b32 v92, v113 offset:1056
	ds_read_b32 v93, v113 offset:1052
	ds_read_b32 v94, v113 offset:1048
	ds_read_b32 v95, v113 offset:1044
	s_waitcnt lgkmcnt(0)
	v_subrev_u32_e32 v236, 32, v127
	v_cmp_gt_u32_e32 vcc, s57, v236
	v_add_f32_e32 v112, v64, v80
	v_subrev_u32_e32 v237, 33, v127
	v_cndmask_b32_e32 v112, v166, v112, vcc
	v_cmp_gt_u32_e32 vcc, s57, v237
	v_add_f32_e32 v113, v65, v81
	v_subrev_u32_e32 v236, 34, v127
	v_cndmask_b32_e32 v113, v166, v113, vcc
	v_cmp_gt_u32_e32 vcc, s57, v236
	v_add_f32_e32 v114, v66, v82
	v_subrev_u32_e32 v237, 35, v127
	v_cndmask_b32_e32 v114, v166, v114, vcc
	v_cmp_gt_u32_e32 vcc, s57, v237
	v_add_f32_e32 v115, v67, v83
	v_subrev_u32_e32 v236, 40, v127
	v_cndmask_b32_e32 v115, v166, v115, vcc
	v_cmp_gt_u32_e32 vcc, s57, v236
	v_add_f32_e32 v116, v68, v84
	v_subrev_u32_e32 v237, 41, v127
	v_cndmask_b32_e32 v116, v166, v116, vcc
	v_cmp_gt_u32_e32 vcc, s57, v237
	v_add_f32_e32 v117, v69, v85
	v_subrev_u32_e32 v236, 42, v127
	v_cndmask_b32_e32 v117, v166, v117, vcc
	v_cmp_gt_u32_e32 vcc, s57, v236
	v_add_f32_e32 v118, v70, v86
	v_subrev_u32_e32 v237, 43, v127
	v_cndmask_b32_e32 v118, v166, v118, vcc
	v_cmp_gt_u32_e32 vcc, s57, v237
	v_add_f32_e32 v119, v71, v87
	v_subrev_u32_e32 v236, 48, v127
	v_cndmask_b32_e32 v119, v166, v119, vcc
	v_cmp_gt_u32_e32 vcc, s57, v236
	v_add_f32_e32 v120, v72, v88
	v_subrev_u32_e32 v237, 49, v127
	v_cndmask_b32_e32 v120, v166, v120, vcc
	v_cmp_gt_u32_e32 vcc, s57, v237
	v_add_f32_e32 v121, v73, v89
	v_subrev_u32_e32 v236, 50, v127
	v_cndmask_b32_e32 v121, v166, v121, vcc
	v_cmp_gt_u32_e32 vcc, s57, v236
	v_add_f32_e32 v122, v74, v90
	v_subrev_u32_e32 v237, 51, v127
	v_cndmask_b32_e32 v122, v166, v122, vcc
	v_cmp_gt_u32_e32 vcc, s57, v237
	v_add_f32_e32 v123, v75, v91
	v_subrev_u32_e32 v236, 56, v127
	v_cndmask_b32_e32 v123, v166, v123, vcc
	v_cmp_gt_u32_e32 vcc, s57, v236
	v_add_f32_e32 v124, v76, v92
	v_subrev_u32_e32 v237, 57, v127
	v_cndmask_b32_e32 v124, v166, v124, vcc
	v_cmp_gt_u32_e32 vcc, s57, v237
	v_add_f32_e32 v125, v77, v93
	v_subrev_u32_e32 v236, 58, v127
	v_cndmask_b32_e32 v125, v166, v125, vcc
	v_cmp_gt_u32_e32 vcc, s57, v236
	v_add_f32_e32 v126, v78, v94
	v_subrev_u32_e32 v237, 59, v127
	v_cndmask_b32_e32 v126, v166, v126, vcc
	v_cmp_gt_u32_e32 vcc, s57, v237
	v_add_f32_e32 v127, v79, v95
	s_nop 0
	v_cndmask_b32_e32 v127, v166, v127, vcc

; __device__ __forceinline__ void bias_mask_tile(f32x16& p0, f32x16& p1, int dq, unsigned W, const float* tbx) {
;     const float NEG = -__builtin_inff();
;     const float* bp = tbx + (dq - 63);
; #pragma unroll
;     for (int r = 0; r < 16; ++r) {
;         const int c = (r & 3) + 8 * (r >> 2);
;         const unsigned r0 = (unsigned)(dq - c), r1 = (unsigned)(dq - c - 32);
;         const float b0 = bp[63 - c], b1 = bp[31 - c];
;         p0[r] = r0 >= W ? NEG : p0[r] + b0;
;         p1[r] = r1 >= W ? NEG : p1[r] + b1;
;         if ((r & 3) == 3) __builtin_amdgcn_sched_barrier(0);
;     }
; }
.LBB0_729:
	s_andn2_b64 vcc, exec, s[4:5]
	s_cbranch_vccnz .LBB0_763
	v_subrev_u32_e32 v127, s10, v174
	v_lshl_add_u32 v113, v127, 2, s29
	ds_read_b32 v64, v113 offset:1280
	ds_read_b32 v65, v113 offset:1276
	ds_read_b32 v66, v113 offset:1272
	ds_read_b32 v67, v113 offset:1268
	ds_read_b32 v68, v113 offset:1248
	ds_read_b32 v69, v113 offset:1244
	ds_read_b32 v70, v113 offset:1240
	ds_read_b32 v71, v113 offset:1236
	ds_read_b32 v72, v113 offset:1216
	ds_read_b32 v73, v113 offset:1212
	ds_read_b32 v74, v113 offset:1208
	ds_read_b32 v75, v113 offset:1204
	ds_read_b32 v76, v113 offset:1184
	ds_read_b32 v77, v113 offset:1180
	ds_read_b32 v78, v113 offset:1176
	ds_read_b32 v79, v113 offset:1172
	s_waitcnt lgkmcnt(0)
	v_cmp_gt_u32_e32 vcc, s57, v127
	v_add_f32_e32 v64, v96, v64
	v_subrev_u32_e32 v237, 1, v127
	v_cndmask_b32_e32 v64, v166, v64, vcc
	v_cmp_gt_u32_e32 vcc, s57, v237
	v_add_f32_e32 v65, v97, v65
	v_subrev_u32_e32 v236, 2, v127
	v_cndmask_b32_e32 v65, v166, v65, vcc
	v_cmp_gt_u32_e32 vcc, s57, v236
	v_add_f32_e32 v66, v98, v66
	v_subrev_u32_e32 v237, 3, v127
	v_cndmask_b32_e32 v66, v166, v66, vcc
	v_cmp_gt_u32_e32 vcc, s57, v237
	v_add_f32_e32 v67, v99, v67
	v_subrev_u32_e32 v236, 8, v127
	v_cndmask_b32_e32 v67, v166, v67, vcc
	v_cmp_gt_u32_e32 vcc, s57, v236
	v_add_f32_e32 v68, v100, v68
	v_subrev_u32_e32 v237, 9, v127
	v_cndmask_b32_e32 v68, v166, v68, vcc
	v_cmp_gt_u32_e32 vcc, s57, v237
	v_add_f32_e32 v69, v101, v69
	v_subrev_u32_e32 v236, 10, v127
	v_cndmask_b32_e32 v69, v166, v69, vcc
	v_cmp_gt_u32_e32 vcc, s57, v236
	v_add_f32_e32 v70, v102, v70
	v_subrev_u32_e32 v237, 11, v127
	v_cndmask_b32_e32 v70, v166, v70, vcc
	v_cmp_gt_u32_e32 vcc, s57, v237
	v_add_f32_e32 v71, v103, v71
	v_subrev_u32_e32 v236, 16, v127
	v_cndmask_b32_e32 v71, v166, v71, vcc
	v_cmp_gt_u32_e32 vcc, s57, v236
	v_add_f32_e32 v72, v104, v72
	v_subrev_u32_e32 v237, 17, v127
	v_cndmask_b32_e32 v72, v166, v72, vcc
	v_cmp_gt_u32_e32 vcc, s57, v237
	v_add_f32_e32 v73, v105, v73
	v_subrev_u32_e32 v236, 18, v127
	v_cndmask_b32_e32 v73, v166, v73, vcc
	v_cmp_gt_u32_e32 vcc, s57, v236
	v_add_f32_e32 v74, v106, v74
	v_subrev_u32_e32 v237, 19, v127
	v_cndmask_b32_e32 v74, v166, v74, vcc
	v_cmp_gt_u32_e32 vcc, s57, v237
	v_add_f32_e32 v75, v107, v75
	v_subrev_u32_e32 v236, 24, v127
	v_cndmask_b32_e32 v75, v166, v75, vcc
	v_cmp_gt_u32_e32 vcc, s57, v236
	v_add_f32_e32 v76, v108, v76
	v_subrev_u32_e32 v237, 25, v127
	v_cndmask_b32_e32 v76, v166, v76, vcc
	v_cmp_gt_u32_e32 vcc, s57, v237
	v_add_f32_e32 v77, v109, v77
	v_subrev_u32_e32 v236, 26, v127
	v_cndmask_b32_e32 v77, v166, v77, vcc
	v_cmp_gt_u32_e32 vcc, s57, v236
	v_add_f32_e32 v78, v110, v78
	v_subrev_u32_e32 v237, 27, v127
	v_cndmask_b32_e32 v78, v166, v78, vcc
	v_cmp_gt_u32_e32 vcc, s57, v237
	v_add_f32_e32 v79, v111, v79
	s_nop 0
	v_cndmask_b32_e32 v79, v166, v79, vcc
	ds_read_b32 v96, v113 offset:1152
	ds_read_b32 v97, v113 offset:1148
	ds_read_b32 v98, v113 offset:1144
	ds_read_b32 v99, v113 offset:1140
	ds_read_b32 v100, v113 offset:1120
	ds_read_b32 v101, v113 offset:1116
	ds_read_b32 v102, v113 offset:1112
	ds_read_b32 v103, v113 offset:1108
	ds_read_b32 v104, v113 offset:1088
	ds_read_b32 v105, v113 offset:1084
	ds_read_b32 v106, v113 offset:1080
	ds_read_b32 v107, v113 offset:1076
	ds_read_b32 v108, v113 offset:1056
	ds_read_b32 v109, v113 offset:1052
	ds_read_b32 v110, v113 offset:1048
	ds_read_b32 v111, v113 offset:1044
	s_waitcnt lgkmcnt(0)
	v_subrev_u32_e32 v236, 32, v127
	v_cmp_gt_u32_e32 vcc, s57, v236
	v_add_f32_e32 v112, v80, v96
	v_subrev_u32_e32 v237, 33, v127
	v_cndmask_b32_e32 v112, v166, v112, vcc
	v_cmp_gt_u32_e32 vcc, s57, v237
	v_add_f32_e32 v113, v81, v97
	v_subrev_u32_e32 v236, 34, v127
	v_cndmask_b32_e32 v113, v166, v113, vcc
	v_cmp_gt_u32_e32 vcc, s57, v236
	v_add_f32_e32 v114, v82, v98
	v_subrev_u32_e32 v237, 35, v127
	v_cndmask_b32_e32 v114, v166, v114, vcc
	v_cmp_gt_u32_e32 vcc, s57, v237
	v_add_f32_e32 v115, v83, v99
	v_subrev_u32_e32 v236, 40, v127
	v_cndmask_b32_e32 v115, v166, v115, vcc
	v_cmp_gt_u32_e32 vcc, s57, v236
	v_add_f32_e32 v116, v84, v100
	v_subrev_u32_e32 v237, 41, v127
	v_cndmask_b32_e32 v116, v166, v116, vcc
	v_cmp_gt_u32_e32 vcc, s57, v237
	v_add_f32_e32 v117, v85, v101
	v_subrev_u32_e32 v236, 42, v127
	v_cndmask_b32_e32 v117, v166, v117, vcc
	v_cmp_gt_u32_e32 vcc, s57, v236
	v_add_f32_e32 v118, v86, v102
	v_subrev_u32_e32 v237, 43, v127
	v_cndmask_b32_e32 v118, v166, v118, vcc
	v_cmp_gt_u32_e32 vcc, s57, v237
	v_add_f32_e32 v119, v87, v103
	v_subrev_u32_e32 v236, 48, v127
	v_cndmask_b32_e32 v119, v166, v119, vcc
	v_cmp_gt_u32_e32 vcc, s57, v236
	v_add_f32_e32 v120, v88, v104
	v_subrev_u32_e32 v237, 49, v127
	v_cndmask_b32_e32 v120, v166, v120, vcc
	v_cmp_gt_u32_e32 vcc, s57, v237
	v_add_f32_e32 v121, v89, v105
	v_subrev_u32_e32 v236, 50, v127
	v_cndmask_b32_e32 v121, v166, v121, vcc
	v_cmp_gt_u32_e32 vcc, s57, v236
	v_add_f32_e32 v122, v90, v106
	v_subrev_u32_e32 v237, 51, v127
	v_cndmask_b32_e32 v122, v166, v122, vcc
	v_cmp_gt_u32_e32 vcc, s57, v237
	v_add_f32_e32 v123, v91, v107
	v_subrev_u32_e32 v236, 56, v127
	v_cndmask_b32_e32 v123, v166, v123, vcc
	v_cmp_gt_u32_e32 vcc, s57, v236
	v_add_f32_e32 v124, v92, v108
	v_subrev_u32_e32 v237, 57, v127
	v_cndmask_b32_e32 v124, v166, v124, vcc
	v_cmp_gt_u32_e32 vcc, s57, v237
	v_add_f32_e32 v125, v93, v109
	v_subrev_u32_e32 v236, 58, v127
	v_cndmask_b32_e32 v125, v166, v125, vcc
	v_cmp_gt_u32_e32 vcc, s57, v236
	v_add_f32_e32 v126, v94, v110
	v_subrev_u32_e32 v237, 59, v127
	v_cndmask_b32_e32 v126, v166, v126, vcc
	v_cmp_gt_u32_e32 vcc, s57, v237
	v_add_f32_e32 v127, v95, v111
	s_nop 0
	v_cndmask_b32_e32 v127, v166, v127, vcc

; __device__ __forceinline__ void bias_mask_tile(f32x16& p0, f32x16& p1, int dq, unsigned W, const float* tbx) {
;     const float NEG = -__builtin_inff();
;     const float* bp = tbx + (dq - 63);
; #pragma unroll
;     for (int r = 0; r < 16; ++r) {
;         const int c = (r & 3) + 8 * (r >> 2);
;         const unsigned r0 = (unsigned)(dq - c), r1 = (unsigned)(dq - c - 32);
;         const float b0 = bp[63 - c], b1 = bp[31 - c];
;         p0[r] = r0 >= W ? NEG : p0[r] + b0;
;         p1[r] = r1 >= W ? NEG : p1[r] + b1;
;         if ((r & 3) == 3) __builtin_amdgcn_sched_barrier(0);
;     }
; }
.LBB0_907:
	s_andn2_b64 vcc, exec, s[2:3]
	s_cbranch_vccnz .LBB0_941
	v_subrev_u32_e32 v127, s0, v174
	v_lshl_add_u32 v113, v127, 2, s29
	ds_read_b32 v96, v113 offset:1280
	ds_read_b32 v97, v113 offset:1276
	ds_read_b32 v98, v113 offset:1272
	ds_read_b32 v99, v113 offset:1268
	ds_read_b32 v100, v113 offset:1248
	ds_read_b32 v101, v113 offset:1244
	ds_read_b32 v102, v113 offset:1240
	ds_read_b32 v103, v113 offset:1236
	ds_read_b32 v104, v113 offset:1216
	ds_read_b32 v105, v113 offset:1212
	ds_read_b32 v106, v113 offset:1208
	ds_read_b32 v107, v113 offset:1204
	ds_read_b32 v108, v113 offset:1184
	ds_read_b32 v109, v113 offset:1180
	ds_read_b32 v110, v113 offset:1176
	ds_read_b32 v111, v113 offset:1172
	s_waitcnt lgkmcnt(0)
	v_cmp_gt_u32_e32 vcc, s57, v127
	v_add_f32_e32 v96, v80, v96
	v_subrev_u32_e32 v237, 1, v127
	v_cndmask_b32_e32 v96, v166, v96, vcc
	v_cmp_gt_u32_e32 vcc, s57, v237
	v_add_f32_e32 v97, v81, v97
	v_subrev_u32_e32 v236, 2, v127
	v_cndmask_b32_e32 v97, v166, v97, vcc
	v_cmp_gt_u32_e32 vcc, s57, v236
	v_add_f32_e32 v98, v82, v98
	v_subrev_u32_e32 v237, 3, v127
	v_cndmask_b32_e32 v98, v166, v98, vcc
	v_cmp_gt_u32_e32 vcc, s57, v237
	v_add_f32_e32 v99, v83, v99
	v_subrev_u32_e32 v236, 8, v127
	v_cndmask_b32_e32 v99, v166, v99, vcc
	v_cmp_gt_u32_e32 vcc, s57, v236
	v_add_f32_e32 v100, v84, v100
	v_subrev_u32_e32 v237, 9, v127
	v_cndmask_b32_e32 v100, v166, v100, vcc
	v_cmp_gt_u32_e32 vcc, s57, v237
	v_add_f32_e32 v101, v85, v101
	v_subrev_u32_e32 v236, 10, v127
	v_cndmask_b32_e32 v101, v166, v101, vcc
	v_cmp_gt_u32_e32 vcc, s57, v236
	v_add_f32_e32 v102, v86, v102
	v_subrev_u32_e32 v237, 11, v127
	v_cndmask_b32_e32 v102, v166, v102, vcc
	v_cmp_gt_u32_e32 vcc, s57, v237
	v_add_f32_e32 v103, v87, v103
	v_subrev_u32_e32 v236, 16, v127
	v_cndmask_b32_e32 v103, v166, v103, vcc
	v_cmp_gt_u32_e32 vcc, s57, v236
	v_add_f32_e32 v104, v88, v104
	v_subrev_u32_e32 v237, 17, v127
	v_cndmask_b32_e32 v104, v166, v104, vcc
	v_cmp_gt_u32_e32 vcc, s57, v237
	v_add_f32_e32 v105, v89, v105
	v_subrev_u32_e32 v236, 18, v127
	v_cndmask_b32_e32 v105, v166, v105, vcc
	v_cmp_gt_u32_e32 vcc, s57, v236
	v_add_f32_e32 v106, v90, v106
	v_subrev_u32_e32 v237, 19, v127
	v_cndmask_b32_e32 v106, v166, v106, vcc
	v_cmp_gt_u32_e32 vcc, s57, v237
	v_add_f32_e32 v107, v91, v107
	v_subrev_u32_e32 v236, 24, v127
	v_cndmask_b32_e32 v107, v166, v107, vcc
	v_cmp_gt_u32_e32 vcc, s57, v236
	v_add_f32_e32 v108, v92, v108
	v_subrev_u32_e32 v237, 25, v127
	v_cndmask_b32_e32 v108, v166, v108, vcc
	v_cmp_gt_u32_e32 vcc, s57, v237
	v_add_f32_e32 v109, v93, v109
	v_subrev_u32_e32 v236, 26, v127
	v_cndmask_b32_e32 v109, v166, v109, vcc
	v_cmp_gt_u32_e32 vcc, s57, v236
	v_add_f32_e32 v110, v94, v110
	v_subrev_u32_e32 v237, 27, v127
	v_cndmask_b32_e32 v110, v166, v110, vcc
	v_cmp_gt_u32_e32 vcc, s57, v237
	v_add_f32_e32 v111, v95, v111
	s_nop 0
	v_cndmask_b32_e32 v111, v166, v111, vcc
	ds_read_b32 v80, v113 offset:1152
	ds_read_b32 v81, v113 offset:1148
	ds_read_b32 v82, v113 offset:1144
	ds_read_b32 v83, v113 offset:1140
	ds_read_b32 v84, v113 offset:1120
	ds_read_b32 v85, v113 offset:1116
	ds_read_b32 v86, v113 offset:1112
	ds_read_b32 v87, v113 offset:1108
	ds_read_b32 v88, v113 offset:1088
	ds_read_b32 v89, v113 offset:1084
	ds_read_b32 v90, v113 offset:1080
	ds_read_b32 v91, v113 offset:1076
	ds_read_b32 v92, v113 offset:1056
	ds_read_b32 v93, v113 offset:1052
	ds_read_b32 v94, v113 offset:1048
	ds_read_b32 v95, v113 offset:1044
	s_waitcnt lgkmcnt(0)
	v_subrev_u32_e32 v236, 32, v127
	v_cmp_gt_u32_e32 vcc, s57, v236
	v_add_f32_e32 v112, v64, v80
	v_subrev_u32_e32 v237, 33, v127
	v_cndmask_b32_e32 v112, v166, v112, vcc
	v_cmp_gt_u32_e32 vcc, s57, v237
	v_add_f32_e32 v113, v65, v81
	v_subrev_u32_e32 v236, 34, v127
	v_cndmask_b32_e32 v113, v166, v113, vcc
	v_cmp_gt_u32_e32 vcc, s57, v236
	v_add_f32_e32 v114, v66, v82
	v_subrev_u32_e32 v237, 35, v127
	v_cndmask_b32_e32 v114, v166, v114, vcc
	v_cmp_gt_u32_e32 vcc, s57, v237
	v_add_f32_e32 v115, v67, v83
	v_subrev_u32_e32 v236, 40, v127
	v_cndmask_b32_e32 v115, v166, v115, vcc
	v_cmp_gt_u32_e32 vcc, s57, v236
	v_add_f32_e32 v116, v68, v84
	v_subrev_u32_e32 v237, 41, v127
	v_cndmask_b32_e32 v116, v166, v116, vcc
	v_cmp_gt_u32_e32 vcc, s57, v237
	v_add_f32_e32 v117, v69, v85
	v_subrev_u32_e32 v236, 42, v127
	v_cndmask_b32_e32 v117, v166, v117, vcc
	v_cmp_gt_u32_e32 vcc, s57, v236
	v_add_f32_e32 v118, v70, v86
	v_subrev_u32_e32 v237, 43, v127
	v_cndmask_b32_e32 v118, v166, v118, vcc
	v_cmp_gt_u32_e32 vcc, s57, v237
	v_add_f32_e32 v119, v71, v87
	v_subrev_u32_e32 v236, 48, v127
	v_cndmask_b32_e32 v119, v166, v119, vcc
	v_cmp_gt_u32_e32 vcc, s57, v236
	v_add_f32_e32 v120, v72, v88
	v_subrev_u32_e32 v237, 49, v127
	v_cndmask_b32_e32 v120, v166, v120, vcc
	v_cmp_gt_u32_e32 vcc, s57, v237
	v_add_f32_e32 v121, v73, v89
	v_subrev_u32_e32 v236, 50, v127
	v_cndmask_b32_e32 v121, v166, v121, vcc
	v_cmp_gt_u32_e32 vcc, s57, v236
	v_add_f32_e32 v122, v74, v90
	v_subrev_u32_e32 v237, 51, v127
	v_cndmask_b32_e32 v122, v166, v122, vcc
	v_cmp_gt_u32_e32 vcc, s57, v237
	v_add_f32_e32 v123, v75, v91
	v_subrev_u32_e32 v236, 56, v127
	v_cndmask_b32_e32 v123, v166, v123, vcc
	v_cmp_gt_u32_e32 vcc, s57, v236
	v_add_f32_e32 v124, v76, v92
	v_subrev_u32_e32 v237, 57, v127
	v_cndmask_b32_e32 v124, v166, v124, vcc
	v_cmp_gt_u32_e32 vcc, s57, v237
	v_add_f32_e32 v125, v77, v93
	v_subrev_u32_e32 v236, 58, v127
	v_cndmask_b32_e32 v125, v166, v125, vcc
	v_cmp_gt_u32_e32 vcc, s57, v236
	v_add_f32_e32 v126, v78, v94
	v_subrev_u32_e32 v237, 59, v127
	v_cndmask_b32_e32 v126, v166, v126, vcc
	v_cmp_gt_u32_e32 vcc, s57, v237
	v_add_f32_e32 v127, v79, v95
	s_nop 0
	v_cndmask_b32_e32 v127, v166, v127, vcc
